# W_down conversion tile order re-mapped (output pieces of the tiles in flight spread over the 16 KiB row, 512 B pitch) on top of v058
# baseline (speedup 1.0000x reference)
.LBB0_333:
	s_cmpk_gt_i32 s24, 0xfff
	v_mbcnt_lo_u32_b32 v166, -1, 0
	v_mbcnt_hi_u32_b32 v166, -1, v166
	s_cbranch_scc1 .LBB0_340
	s_lshr_b32 s0, s24, 5
	s_lshl_b32 s0, s0, 7
	s_and_b32 s24, s24, 31
	s_or_b32 s24, s24, s0
	v_ashrrev_i32_e32 v1, 3, v166
	v_or_b32_e32 v4, 1, v1
	v_and_b32_e32 v2, -2, v1
	v_ashrrev_i32_e32 v5, 31, v4
	v_lshlrev_b64 v[132:133], 11, v[4:5]
	v_add_u32_e32 v4, 9, v2
	v_ashrrev_i32_e32 v5, 31, v4
	v_ashrrev_i32_e32 v3, 31, v2
	v_lshlrev_b64 v[136:137], 11, v[4:5]
	v_add_u32_e32 v4, 17, v2
	v_lshlrev_b64 v[130:131], 11, v[2:3]
	s_mov_b64 s[0:1], 0x4000
	v_ashrrev_i32_e32 v5, 31, v4
	v_lshl_add_u64 v[134:135], v[130:131], 0, s[0:1]
	s_mov_b64 s[0:1], 0x8000
	v_lshlrev_b64 v[140:141], 11, v[4:5]
	v_add_u32_e32 v4, 25, v2
	v_lshl_add_u64 v[138:139], v[130:131], 0, s[0:1]
	s_mov_b64 s[0:1], 0xc000
	v_ashrrev_i32_e32 v5, 31, v4
	v_lshl_add_u64 v[142:143], v[130:131], 0, s[0:1]
	v_lshlrev_b64 v[144:145], 11, v[4:5]
	s_mov_b64 s[0:1], 0x10000
	v_add_u32_e32 v4, 33, v2
	v_lshl_add_u64 v[146:147], v[130:131], 0, s[0:1]
	v_ashrrev_i32_e32 v5, 31, v4
	s_mov_b64 s[0:1], 0x14000
	v_lshlrev_b64 v[148:149], 11, v[4:5]
	v_lshl_add_u64 v[150:151], v[130:131], 0, s[0:1]
	v_add_u32_e32 v4, 41, v2
	s_mov_b64 s[0:1], 0x18000
	v_lshlrev_b32_e32 v0, 2, v166
	v_ashrrev_i32_e32 v5, 31, v4
	v_lshl_add_u64 v[154:155], v[130:131], 0, s[0:1]
	s_mov_b64 s[0:1], 0x1c000
	v_and_b32_e32 v0, 60, v0
	v_lshlrev_b64 v[152:153], 11, v[4:5]
	v_add_u32_e32 v4, 49, v2
	v_lshl_add_u64 v[158:159], v[130:131], 0, s[0:1]
	v_add_u32_e32 v2, 57, v2
	v_readlane_b32 s0, v254, 3
	v_mov_b32_e32 v129, 0
	v_ashrrev_i32_e32 v5, 31, v4
	v_ashrrev_i32_e32 v3, 31, v2
	s_lshl_b32 s0, s0, 6
	v_readlane_b32 s1, v254, 13
	v_lshlrev_b32_e32 v162, 2, v0
	s_mov_b32 s8, 32
	v_lshlrev_b64 v[156:157], 11, v[4:5]
	v_lshlrev_b64 v[160:161], 11, v[2:3]
	s_mov_b32 s9, 64
	s_movk_i32 s10, 0x800
	s_lshl_b32 s11, s24, 6
	s_movk_i32 s12, 0x1000
	v_mov_b32_e32 v164, v162
	v_mov_b32_e32 v165, v129
	s_movk_i32 s13, 0x70
	s_movk_i32 s14, 0x50
	s_movk_i32 s15, 0x60
	s_branch .LBB0_336
.LBB0_335:
	s_add_i32 s24, s24, s9
	s_add_i32 s11, s11, s12
	s_bitcmp0_b32 s24, 6
	s_cbranch_scc1 .LBB0_340
